# v29 + first 128 up-projection units run on the idle workgroups of the last group's output-projection phase; the up-projection phase enumerates the remaining 2754 (11 rounds instead of 12)
# speedup vs baseline: 1.0367x; 1.0026x over previous
;     __host__ __device__ bool next(int i, Unit& u) const {
;         const long L = (long)i * G + c; if (L >= nwg) return false;
;         int wgid = (int)L; { const int q = nwg / NXCD, r = nwg % NXCD, xcd = wgid % NXCD, off = wgid / NXCD; wgid = (xcd < r ? xcd * (q + 1) : r * (q + 1) + (xcd - r) * q) + off; }
;         const int nig = WGM * nN, gid = wgid / nig, fm = gid * WGM, gsz = (nM - fm) < WGM ? (nM - fm) : WGM;
;         u.pm = fm + ((wgid % nig) % gsz); u.pn = (wgid % nig) / gsz; return true;
; template <class Epi, class Sched, bool ALIGN_EPI = false, bool SP2 = false>
; __device__ __forceinline__ void gemm_phase(const int tid, PG8_LAS unsigned char* lds, const Gemm g, const Sched& S, const Epi& E) {
;     ...
;     const int K = g.ld ? g.ld : g.K, nt = g.K / BK;
;     unsigned voffA[2], voffB[2];
; #pragma unroll
;     for (int i = 0; i < 2; ++i) { int R, C; stage_rc(tid * 16 + i * 8192, R, C); const int Rb = Epi::PERM ? ((R & ~31) + perm32(R & 31)) : R;
;         voffA[i] = (unsigned)(R * K + C) * 2u; voffB[i] = (unsigned)(Rb * K + C) * 2u; }
;     const size_t kstep = (size_t)(BK * 2);
;     const size_t hstep = (size_t)HALF * K * 2;
;     const size_t tstep = 2 * hstep;
;     const unsigned ldsw = (unsigned)wid * 1024u;
;     const int aoff = lds_byte(wr * 64 + fr, fq * 8), boff = lds_byte(wc * 32 + fr, fq * 8);
;     ...
;     Unit cur, nxt; int ui = 0;
;     if (!S.next(0, cur)) return;
;     f32x4 acc[2][2][4][2];
; #pragma unroll
;     for (int a = 0; a < 2; ++a)
; #pragma unroll
;         for (int b = 0; b < 2; ++b)
; #pragma unroll
;             for (int m = 0; m < 4; ++m)
; #pragma unroll
;                 for (int n = 0; n < 2; ++n) acc[a][b][m][n] = (f32x4){0.f, 0.f, 0.f, 0.f};
;     bf16x8 At[4][2], B0[2][2], B1[2][2];
;     const char* cA = (const char*)g.A + (size_t)cur.pm * tstep + cur.offA; const char* cB = (const char*)g.Bt + (size_t)cur.pn * tstep + cur.offB;
;     S.a_ready(cur);
;     if constexpr (SP2) {
;         PG8_STAGE(PG8_SB(0, 0), cB, voffB); PG8_STAGE(PG8_SB(0, 1), cB + hstep, voffB); PG8_STAGE(PG8_SA(0, 0), cA, voffA); PG8_STAGE(PG8_SA(0, 1), cA + hstep, voffA);
;         if (wr == 1) PG8_BAR;
;         PG8_WAIT_V(2); PG8_BAR;
;         PG8_STAGE(PG8_SB(1, 0), cB + kstep, voffB); PG8_STAGE(PG8_SA(1, 0), cA + kstep, voffA); PG8_STAGE(PG8_SB(1, 1), cB + hstep + kstep, voffB);
;         PG8_WAIT_V(6); PG8_BAR;
;     } else {
.LBB0_170:
	s_and_b64 vcc, exec, s[4:5]
	s_cbranch_vccz .LBB0_195
	s_mov_b32 s98, 0xb42
	s_movk_i32 s99, 0x168
	s_mov_b32 s100, 0
	s_cmp_lg_u32 s92, 0x100
	s_cbranch_scc1 .Lk9_go
	s_mov_b32 s98, 0xac2
	s_movk_i32 s99, 0x158
	s_movk_i32 s100, 0x80
.Lk9_go:
	s_waitcnt vmcnt(0)
	v_mov_b32_e32 v0, v228
	s_mov_b32 s0, s92
	v_mov_b32_e32 v0, v228
	s_mov_b32 s1, s82
	v_mov_b32_e32 v14, v228
	s_cmp_ge_i32 s1, s98
	v_readfirstlane_b32 s38, v14
	s_cbranch_scc1 .LBB0_195
	s_ashr_i32 s2, s1, 31
	s_lshr_b32 s3, s2, 29
	s_add_i32 s10, s1, s3
	s_and_b32 s3, s10, -8
	s_sub_i32 s3, s1, s3
	s_cmp_gt_i32 s3, 1
	s_mov_b64 s[6:7], -1
	s_cbranch_scc0 .LBB0_174
	s_mul_i32 s4, s3, s99
	s_or_b32 s12, s4, 2
	s_mov_b64 s[6:7], 0
.LBB0_174:
	s_load_dwordx2 s[4:5], s[18:19], 0xf0
	s_mov_b64 s[66:67], s[18:19]
	s_andn2_b64 vcc, exec, s[6:7]
	s_ashr_i32 s6, s10, 3
	s_cbranch_vccnz .LBB0_176
	s_mul_i32 s12, s3, s99
	s_add_i32 s12, s12, s3
.LBB0_176:
	v_ashrrev_i32_e32 v1, 31, v14
	v_lshrrev_b32_e32 v1, 26, v1
	v_add_u32_e32 v1, v14, v1
	v_ashrrev_i32_e32 v8, 6, v1
	v_bfe_i32 v1, v14, 27, 1
	v_lshlrev_b32_e32 v0, 4, v14
	v_lshrrev_b32_e32 v1, 22, v1
	v_add_u32_e32 v1, v0, v1
	v_and_b32_e32 v1, 0xfffffc00, v1
	v_sub_u32_e32 v1, v0, v1
	v_lshrrev_b32_e32 v2, 4, v1
	v_bitop3_b32 v2, v2, v1, 32 bitop3:0x6c
	v_ashrrev_i32_e32 v1, 31, v1
	v_lshrrev_b32_e32 v1, 26, v1
	v_add_u32_e32 v1, v2, v1
	s_mul_i32 s7, s96, 0x2400000
	v_ashrrev_i32_e32 v9, 6, v1
	s_mul_hi_i32 s3, s96, 0x2400000
	s_waitcnt lgkmcnt(0)
	s_add_u32 s7, s4, s7
	v_lshlrev_b32_e32 v3, 3, v8
	v_mul_i32_i24_e32 v4, 64, v9
	s_addc_u32 s16, s5, s3
	v_and_b32_e32 v3, -16, v3
	v_sub_u32_e32 v2, v2, v4
	s_add_u32 s3, s4, 0x8300000
	v_add_u32_e32 v1, v9, v3
	v_lshlrev_b32_e32 v3, 5, v8
	v_ashrrev_i16_sdwa v2, v231, sext(v2) dst_sel:DWORD dst_unused:UNUSED_PAD src0_sel:DWORD src1_sel:BYTE_0
	s_addc_u32 s10, s5, 0
	v_and_b32_e32 v3, 32, v3
	v_bfe_i32 v10, v2, 0, 16
	s_add_u32 s11, s7, 0xd780000
	v_and_b32_e32 v5, 3, v9
	s_mov_b32 s7, 0x1fffe0
	v_add_lshl_u32 v3, v3, v10, 1
	v_add_u32_e32 v0, 0x2000, v0
	v_lshlrev_b32_e32 v2, 1, v1
	v_lshrrev_b32_e32 v4, 2, v1
	v_and_or_b32 v5, v1, s7, v5
	v_lshl_add_u32 v130, v1, 11, v3
	v_ashrrev_i32_e32 v1, 31, v0
	v_lshrrev_b32_e32 v1, 22, v1
	v_add_u32_e32 v1, v0, v1
	v_ashrrev_i32_e32 v11, 10, v1
	v_mul_i32_i24_e32 v1, 0x400, v11
	v_sub_u32_e32 v0, v0, v1
	v_and_b32_e32 v2, 24, v2
	v_and_b32_e32 v4, 4, v4
	v_lshrrev_b32_e32 v1, 4, v0
	v_or3_b32 v2, v5, v4, v2
	v_bitop3_b32 v0, v1, v0, 32 bitop3:0x6c
	v_lshl_add_u32 v32, v2, 11, v3
	v_ashrrev_i32_e32 v2, 31, v0
	v_lshrrev_b32_e32 v2, 26, v2
	v_lshlrev_b32_e32 v1, 3, v11
	v_add_u32_e32 v2, v0, v2
	v_and_b32_e32 v1, -16, v1
	v_ashrrev_i32_e32 v12, 6, v2
	s_addc_u32 s18, s16, 0
	v_add_u32_e32 v1, v12, v1
	v_and_b32_e32 v4, 3, v12
	s_add_i32 s6, s12, s6
	s_add_i32 s6, s6, s100
	s_cmp_lg_u32 s99, 0
	s_cselect_b32 s6, s6, s1
	v_and_b32_e32 v2, 0xc0, v2
	v_and_or_b32 v4, v1, s7, v4
	s_mul_hi_i32 s7, s6, 0x2e8ba2e9
	v_sub_u32_e32 v0, v0, v2
	s_lshr_b32 s12, s7, 31
	s_ashr_i32 s7, s7, 5
	v_ashrrev_i16_sdwa v0, v231, sext(v0) dst_sel:DWORD dst_unused:UNUSED_PAD src0_sel:DWORD src1_sel:BYTE_0
	s_add_i32 s7, s7, s12
	v_lshlrev_b32_e32 v3, 5, v11
	v_bfe_i32 v13, v0, 0, 16
	v_lshlrev_b32_e32 v0, 1, v1
	v_lshrrev_b32_e32 v2, 2, v1
	s_lshl_b32 s16, s7, 3
	v_and_b32_e32 v3, 32, v3
	v_and_b32_e32 v0, 24, v0
	v_and_b32_e32 v2, 4, v2
	s_sub_i32 s12, 0x83, s16
	v_or3_b32 v0, v4, v2, v0
	v_add_lshl_u32 v2, v3, v13, 1
	s_min_u32 s17, s12, 8
	s_mulk_i32 s7, 0xb0
	v_lshl_add_u32 v132, v1, 11, v2
	s_sub_i32 s20, s6, s7
	v_cvt_f32_ubyte0_e32 v1, s17
	v_lshl_add_u32 v134, v0, 11, v2
	v_cvt_f32_i32_e32 v0, s20
	v_rcp_iflag_f32_e32 v2, v1
	s_ashr_i32 s40, s38, 6
	s_ashr_i32 s6, s20, 30
	s_ashr_i32 s39, s38, 8
	v_mul_f32_e32 v2, v0, v2
	v_trunc_f32_e32 v2, v2
	v_fma_f32 v0, -v2, v1, v0
	v_cvt_i32_f32_e32 v2, v2
	s_lshl_b32 s19, s40, 10
	s_or_b32 s12, s6, 1
	v_cmp_ge_f32_e64 s[6:7], |v0|, v1
	s_and_b64 s[6:7], s[6:7], exec
	s_cselect_b32 s6, s12, 0
	v_readfirstlane_b32 s7, v2
	s_add_i32 s12, s7, s6
	s_mul_i32 s6, s12, s17
	s_sub_i32 s6, s20, s6
	s_sext_i32_i16 s6, s6
	s_add_i32 s48, s16, s6
	s_ashr_i32 s49, s48, 31
	s_bfe_i64 s[16:17], s[12:13], 0x100000
	s_lshl_b64 s[6:7], s[48:49], 19
	s_lshl_b64 s[16:17], s[16:17], 19
	s_add_u32 s20, s11, s16
	s_addc_u32 s21, s18, s17
	s_add_i32 s33, s19, 0
	s_add_i32 m0, s33, 0x10000
	v_mov_b32_e32 v135, v33
	global_load_lds_dwordx4 v32, s[20:21]
	s_add_i32 m0, s33, 0x12000
	s_add_u32 s16, s20, 0x40000
	global_load_lds_dwordx4 v134, s[20:21]
	s_addc_u32 s17, s21, 0
	s_add_i32 m0, s33, 0x14000
	v_mov_b32_e32 v131, v33
	global_load_lds_dwordx4 v32, s[16:17]
	s_add_i32 m0, s33, 0x16000
	s_add_u32 s50, s3, s6
	s_addc_u32 s51, s10, s7
	s_add_i32 s35, s33, 0x2000
	global_load_lds_dwordx4 v134, s[16:17]
	s_mov_b32 m0, s33
	s_add_u32 s6, s50, 0x40000
	global_load_lds_dwordx4 v130, s[50:51]
	s_mov_b32 m0, s35
	s_addc_u32 s7, s51, 0
	s_add_i32 s36, s33, 0x4000
	global_load_lds_dwordx4 v132, s[50:51]
	s_mov_b32 m0, s36
	s_add_i32 s37, s33, 0x6000
	global_load_lds_dwordx4 v130, s[6:7]
	s_mov_b32 m0, s37
	v_mov_b32_e32 v133, v33
	global_load_lds_dwordx4 v132, s[6:7]
	s_cmp_eq_u32 s39, 1
	v_lshl_add_u64 v[6:7], s[20:21], 0, v[32:33]
	v_lshl_add_u64 v[4:5], s[20:21], 0, v[134:135]
	v_lshl_add_u64 v[0:1], s[50:51], 0, v[130:131]
	s_cselect_b64 s[6:7], -1, 0
	s_cmp_lg_u32 s39, 1
	v_lshl_add_u64 v[2:3], s[50:51], 0, v[132:133]
	s_cbranch_scc1 .LBB0_178
	s_barrier

;     DI bool next(int i, Unit& u) const { if (!S.next(i / 3, u)) return false; const int z = i % 3; u.z = z; u.offA = (unsigned)z * (unsigned)(G0ROWS * 512 * 2); u.offB = (unsigned)z * (unsigned)(524288 * 2); return true; }
;     DI bool next(int i, Unit& u) const { const int j = i * G + c; if (j >= 3 * 4 * NKSL) return false; u.pm = MMAIN / 256 + j / (4 * NKSL); u.pn = (j / NKSL) & 3; const int kh = j % NKSL; u.z = kh; u.offA = (unsigned)(kh * 512); u.offB = (unsigned)(kh * 512); return true; }
;     __host__ __device__ bool next(int i, Unit& u) const {
;         const long L = (long)i * G + c; if (L >= nwg) return false;
;         int wgid = (int)L; { const int q = nwg / NXCD, r = nwg % NXCD, xcd = wgid % NXCD, off = wgid / NXCD; wgid = (xcd < r ? xcd * (q + 1) : r * (q + 1) + (xcd - r) * q) + off; }
;         const int nig = WGM * nN, gid = wgid / nig, fm = gid * WGM, gsz = (nM - fm) < WGM ? (nM - fm) : WGM;
;         u.pm = fm + ((wgid % nig) % gsz); u.pn = (wgid % nig) / gsz; return true;
.LBB0_181:
	s_add_i32 s55, s55, 1
	s_mul_i32 s4, s55, s54
	s_mul_hi_u32 s5, s55, s0
	s_add_i32 s5, s5, s4
	s_mul_i32 s4, s55, s0
	s_add_u32 s44, s4, s1
	s_addc_u32 s45, s5, s2
	s_cmp_lt_u32 s44, s98
	s_cselect_b64 s[4:5], -1, 0
	s_not_b64 vcc, s[4:5]
	s_cbranch_vccnz .LBB0_187
	s_ashr_i32 s40, s44, 31
	s_lshr_b32 s40, s40, 29
	s_add_i32 s42, s44, s40
	s_and_b32 s40, s42, -8
	s_sub_i32 s43, s44, s40
	s_cmp_gt_i32 s43, 1
	s_mov_b64 s[40:41], -1
	s_cbranch_scc0 .LBB0_184
	s_mul_i32 s40, s43, s99
	s_or_b32 s44, s40, 2
	s_mov_b64 s[40:41], 0
.LBB0_184:
	s_andn2_b64 vcc, exec, s[40:41]
	s_cbranch_vccnz .LBB0_186
	s_mul_i32 s44, s43, s99
	s_add_i32 s44, s44, s43
.LBB0_186:
	s_ashr_i32 s40, s42, 3
	s_add_i32 s40, s44, s40
	s_add_i32 s40, s40, s100
	s_mul_hi_i32 s41, s40, 0x2e8ba2e9
	s_lshr_b32 s42, s41, 31
	s_ashr_i32 s41, s41, 5
	s_add_i32 s41, s41, s42
	s_lshl_b32 s42, s41, 3
	s_sub_i32 s43, 0x83, s42
	s_min_i32 s43, s43, 8
	s_abs_i32 s44, s43
	v_cvt_f32_u32_e32 v0, s44
	s_sub_i32 s46, 0, s44
	s_mulk_i32 s41, 0xb0
	s_sub_i32 s41, s40, s41
	v_rcp_iflag_f32_e32 v0, v0
	s_abs_i32 s40, s41
	s_xor_b32 s45, s41, s43
	s_ashr_i32 s45, s45, 31
	v_mul_f32_e32 v0, 0x4f7ffffe, v0
	v_cvt_u32_f32_e32 v0, v0
	s_nop 0
	v_readfirstlane_b32 s47, v0
	s_mul_i32 s46, s46, s47
	s_mul_hi_u32 s46, s47, s46
	s_add_i32 s47, s47, s46
	s_mul_hi_u32 s46, s40, s47
	s_mul_i32 s47, s46, s44
	s_sub_i32 s40, s40, s47
	s_add_i32 s52, s46, 1
	s_sub_i32 s47, s40, s44
	s_cmp_ge_u32 s40, s44
	s_cselect_b32 s46, s52, s46
	s_cselect_b32 s40, s47, s40
	s_add_i32 s47, s46, 1
	s_cmp_ge_u32 s40, s44
	s_cselect_b32 s40, s47, s46
	s_xor_b32 s40, s40, s45
	s_sub_i32 s40, s40, s45
	s_mul_i32 s43, s40, s43
	s_sub_i32 s41, s41, s43
	s_add_i32 s42, s42, s41

; #define TIDV tid_opaque()
; #define BIDX bid_opaque()
; #define GDIM gdim_opaque()
; template <int KIND> DI void run_phase(PARAMS P, int l, int g) {
;     ...
;     else if constexpr (KIND == 7) {
;         { pg8::Gemm gm{(const bf16_t*)((unsigned char*)P.out + DS_MIXB), wl + WL_WOUT, gr, D, D}; pg8::StaticOrder S; S.init(gr, D, GDIM, (BIDX + GDIM / 2) % GDIM);
;           EpiRes E{X + (size_t)gbs * D}; pg8::gemm_phase<EpiRes, pg8::StaticOrder, true, true>(TIDV, lds, gm, S, E); }
;     ...
;     else if constexpr (KIND == 9) { pg8::Gemm gm{XN, wl + WL_WFI, MTOT, 2 * DFF, D}; pg8::StaticOrder S; S.init(MTOT, 2 * DFF, GDIM, BIDX);
;         EpiSwiglu E{gb}; pg8::gemm_phase<EpiSwiglu, pg8::StaticOrder, true, true>(TIDV, lds, gm, S, E); }
.Lk7_entry:
	s_cmp_lg_u32 s92, 0x100
	s_cbranch_scc1 .Lk7_noff
	s_cmp_eq_u32 s31, 7
	s_cbranch_scc0 .Lk7_noff
	s_cmp_eq_u32 s34, 3
	s_cbranch_scc0 .Lk7_noff
	s_cmp_lt_u32 s82, 0x80
	s_cbranch_scc0 .Lk7_noff
	s_movk_i32 s98, 0x80
	s_mov_b32 s99, 0
	s_mov_b32 s100, 0
	s_branch .Lk9_go
